# uq/ukv GEMM pair rebalanced: workgroups with two units of the 384-unit GEMM take one unit of the following 512-unit GEMM, the others three (was two each); otherwise v19
# baseline (speedup 1.0000x reference)
;   DI bool next(int i, Unit& u) const {
;     const long L = (long)i * G + c; if (L >= nwg) return false;
;     int wgid = (int)L; { const int q = nwg / NXCD, r = nwg % NXCD, xcd = wgid % NXCD, off = wgid / NXCD; wgid = (xcd < r ? xcd * (q + 1) : r * (q + 1) + (xcd - r) * q) + off; }
;     const int nig = WGM * nN, gid = wgid / nig, fm = gid * WGM, gsz = (nM - fm) < WGM ? (nM - fm) : WGM;
;     u.pm = fm + ((wgid % nig) % gsz); u.pn = (wgid % nig) / gsz; return true;
; template <class Epi>
; DI void gemm_phase(LAS unsigned char* lds, const Gemm g, const StaticOrder& S, const Epi& E) {
;     ...
;     const bool has_next = S.next(ui + 1, nxt);
.LBB0_832:
	s_add_i32 s58, s58, 1
	v_readlane_b32 s12, v250, 54
	v_readlane_b32 s23, v250, 27
	s_cmp_lg_u32 s16, 8
	s_cbranch_scc1 .Lrb_skip
	s_cmp_lg_u32 s23, 0x100
	s_cbranch_scc1 .Lrb_skip
	v_readlane_b32 s42, v251, 0
	s_nop 3
	s_movk_i32 s43, 0x200
	s_cmp_ge_u32 s42, 0x80
	s_cselect_b32 s23, 0x80, s43
.Lrb_skip:
	s_mul_i32 s12, s58, s12
	s_mul_hi_u32 s13, s58, s23
	s_add_i32 s13, s13, s12
	s_mul_i32 s12, s58, s23
	v_readlane_b32 s23, v251, 0
	v_readlane_b32 s42, v250, 28
	s_add_u32 s12, s12, s23
	v_readlane_b32 s23, v251, 10
	v_readlane_b32 s43, v250, 29
	s_addc_u32 s13, s13, s23
	s_nop 0
	v_mov_b64_e32 v[2:3], s[42:43]
	v_cmp_ge_i64_e32 vcc, s[12:13], v[2:3]
	v_cmp_lt_i64_e64 s[44:45], s[12:13], v[2:3]
	s_cbranch_vccnz .LBB0_838
	s_ashr_i32 s13, s12, 31
	s_lshr_b32 s13, s13, 29
	s_add_i32 s23, s12, s13
	s_and_b32 s13, s23, -8
	s_sub_i32 s42, s12, s13
	v_readlane_b32 s12, v250, 55
	s_cmp_ge_i32 s42, s12
	s_mov_b64 s[12:13], -1
	s_cbranch_scc0 .LBB0_835
	v_readlane_b32 s43, v250, 55
	s_sub_i32 s12, s42, s43
	v_readlane_b32 s13, v250, 56
	s_mul_i32 s12, s12, s13
	v_readlane_b32 s13, v250, 57
	s_mul_i32 s13, s13, s43
	s_add_i32 s43, s12, s13
	s_mov_b64 s[12:13], 0
